# shortened the wave-uniform rescale branch test between the QK and PV MFMAs in attention (section 7.12 idiom): one s_cmp feeds both selects, v_cmp feeds s_cbranch_vccz directly
# speedup vs baseline: 1.0072x; 1.0072x over previous
.LBB0_574:
	s_nop 7
	v_max_f32_e32 v156, v67, v67
	v_max_f32_e32 v157, v66, v66
	v_max_f32_e32 v156, v157, v156
	v_max3_f32 v157, v68, v69, v83
	v_max3_f32 v156, v156, v82, v84
	v_max3_f32 v156, v156, v85, v70
	v_max3_f32 v157, v157, v72, v73
	v_max3_f32 v156, v156, v71, v86
	v_max3_f32 v157, v157, v88, v89
	v_max3_f32 v156, v156, v87, v74
	v_max3_f32 v157, v157, v76, v77
	v_max3_f32 v156, v156, v75, v90
	v_max3_f32 v157, v157, v92, v93
	v_max3_f32 v156, v156, v91, v78
	v_max3_f32 v157, v157, v80, v81
	v_max3_f32 v156, v156, v79, v94
	v_max3_f32 v157, v157, v96, v97
	v_max3_f32 v156, v156, v95, v157
	v_mov_b32_e32 v157, v156
	s_nop 1
	v_permlane32_swap_b32_e32 v156, v157
	s_cmp_eq_u32 s83, 0
	v_max_f32_e32 v157, v157, v157
	v_max_f32_e32 v156, v156, v156
	s_cselect_b64 s[8:9], -1, 0
	s_cselect_b64 s[10:11], 0, -1
	v_max_f32_e32 v156, v156, v157
	s_cbranch_scc1 .Lqtrim_577
	v_cmp_lt_f32_e32 vcc, 0x41000000, v156
	s_cbranch_vccz .LBB0_582
.Lqtrim_577:
	v_max_f32_e32 v157, v156, v156
	s_andn2_b64 vcc, exec, s[10:11]
	v_max_f32_e32 v157, 0, v157
	s_cbranch_vccnz .LBB0_581
	v_exp_f32_e64 v158, -v157
	s_and_saveexec_b64 s[10:11], s[4:5]
	ds_write_b32 v147, v158
	s_or_b64 exec, exec, s[10:11]
	v_mul_f32_e32 v154, v154, v158
	ds_read_b128 v[158:161], v114
	ds_read_b128 v[162:165], v114 offset:32
	ds_read_b128 v[166:169], v114 offset:64
	ds_read_b128 v[170:173], v114 offset:96
	s_waitcnt lgkmcnt(3)
	v_pk_mul_f32 v[4:5], v[4:5], v[160:161]
	s_waitcnt lgkmcnt(2)
	v_pk_mul_f32 v[8:9], v[8:9], v[164:165]
	s_waitcnt lgkmcnt(1)
	v_pk_mul_f32 v[12:13], v[12:13], v[168:169]
	s_waitcnt lgkmcnt(0)
	v_pk_mul_f32 v[16:17], v[16:17], v[172:173]
	v_pk_mul_f32 v[14:15], v[14:15], v[170:171]
	v_pk_mul_f32 v[10:11], v[10:11], v[166:167]
	v_pk_mul_f32 v[6:7], v[6:7], v[162:163]
	v_pk_mul_f32 v[2:3], v[2:3], v[158:159]
	v_pk_mul_f32 v[64:65], v[64:65], v[172:173]
	v_pk_mul_f32 v[60:61], v[60:61], v[168:169]
	v_pk_mul_f32 v[56:57], v[56:57], v[164:165]
	v_pk_mul_f32 v[52:53], v[52:53], v[160:161]
	v_pk_mul_f32 v[62:63], v[62:63], v[170:171]
	v_pk_mul_f32 v[58:59], v[58:59], v[166:167]
	v_pk_mul_f32 v[54:55], v[54:55], v[162:163]
	v_pk_mul_f32 v[50:51], v[50:51], v[158:159]
	v_pk_mul_f32 v[48:49], v[48:49], v[172:173]
	v_pk_mul_f32 v[44:45], v[44:45], v[168:169]
	v_pk_mul_f32 v[40:41], v[40:41], v[164:165]
	v_pk_mul_f32 v[36:37], v[36:37], v[160:161]
	v_pk_mul_f32 v[46:47], v[46:47], v[170:171]
	v_pk_mul_f32 v[42:43], v[42:43], v[166:167]
	v_pk_mul_f32 v[38:39], v[38:39], v[162:163]
	v_pk_mul_f32 v[34:35], v[34:35], v[158:159]
	v_pk_mul_f32 v[32:33], v[32:33], v[172:173]
	v_pk_mul_f32 v[28:29], v[28:29], v[168:169]
	v_pk_mul_f32 v[24:25], v[24:25], v[164:165]
	v_pk_mul_f32 v[20:21], v[20:21], v[160:161]
	v_pk_mul_f32 v[30:31], v[30:31], v[170:171]
	v_pk_mul_f32 v[26:27], v[26:27], v[166:167]
	v_pk_mul_f32 v[22:23], v[22:23], v[162:163]
	v_pk_mul_f32 v[18:19], v[18:19], v[158:159]
